# 3/8 of the workgroups run the per-wave dilated-mixture class first, then the cooperative classes
# baseline (speedup 1.0000x reference)
; #define IDX() int tid = threadIdx.x, bid = blockIdx.x, G = gridDim.x; asm volatile("" : "+v"(tid)); asm volatile("" : "+s"(bid), "+s"(G)); \
;     const int lane = tid & 63, wave = __builtin_amdgcn_readfirstlane(tid >> 6), gw = bid * NWAVES + wave, NGW = G * NWAVES; (void)lane; (void)gw; (void)NGW; (void)wave
; template <int PHM, int ATTM> __global__ void __launch_bounds__(NWAVES * 64, 2) fwd_kernel(Args args) {
;     ...
;         if (IN(pb + 4) && EN(5)) for (int rep = 0; rep < (DUP_PHASE == 5 ? 2 : 1); ++rep, (DUP_PHASE == 5 ? xcd_barrier(bar) : (void)0)) { IDX();
;             attention_phase<ATTM>(layer, lane, rep, lds, wave); }
.Lmy_xc_known:
	s_mov_b32 s99, 0
	s_cmp_le_i32 s68, s4
	s_cselect_b64 s[2:3], -1, 0
	s_and_b64 s[4:5], s[2:3], s[14:15]
	s_mov_b64 s[2:3], -1
	s_and_b64 vcc, exec, s[4:5]
	s_cbranch_vccnz .LBB0_546
	v_readlane_b32 s2, v255, 20
	s_add_i32 s4, s2, 6
	s_mov_b64 s[2:3], 0

; #define LAS __attribute__((address_space(3)))
; __device__ __forceinline__ unsigned xb_xcc_id() { return (unsigned)__builtin_amdgcn_s_getreg((3 << 11) | 20) & 0xFu; }
; __device__ __forceinline__ float wave_sum(float v) { v += lx<1>(v); v += lx<2>(v); v += lx<4>(v); v += lx<8>(v); v += lx<16>(v); return half_sum(v); }
; #define ARG_IN(i) ((const float*)karg64(8 * (i)))
; #define ARG_WS() ((unsigned char*)karg64(8 * 19))
; #define WG_DRAW(cls, q) LAS int* slot = (LAS int*)(lds + MISC_OFF + 64); \
;         if (threadIdx.x == 0) *slot = (int)__hip_atomic_fetch_add(XQ_HEAD(cls, q), 1u, RLX_AGENT); \
;         __syncthreads(); const int it = *slot; __syncthreads();
; template <int ATTM> __device__ __forceinline__ void attention_phase(int layer, int lane, int rep, LAS unsigned char* lds, int wave) {
;     asm volatile("" : "+s"(wave));
;     ...
;     if ((ATTM & 2) && PK(2)) {
; #pragma unroll 1
;         for (int qq = 0; qq < 8; ++qq) { const int q = ((int)(xb_xcc_id() & 7u) + qq) & 7;
;             for (;;) { WG_DRAW(0, q); if (it >= 32) break;
;                 unsigned char* ws = ARG_WS(); int tid = threadIdx.x; asm volatile("" : "+v"(tid));
;                 const float* lamv = ARG_IN(A_LAM) + (size_t)layer * 4 * 64;
;                 const float lam_init = 0.8f - 0.6f * __builtin_amdgcn_exp2f(-0.3f * 1.4426950408889634f * (float)layer);
;                 const float sa = wave_sum(lamv[lane] * lamv[64 + lane]), sb = wave_sum(lamv[128 + lane] * lamv[192 + lane]);
;                 const float lam = __builtin_amdgcn_exp2f(1.4426950408889634f * sa) - __builtin_amdgcn_exp2f(1.4426950408889634f * sb) + lam_init;
;                 dif_coop(WSP(bf16, WS_PROJ), ws + WS_VTB, WSP(bf16, WS_O), lam, ARG_IN(A_SUBG) + (size_t)layer * 128, 1.f - lam_init, q, 31 - it, lds, tid); } } }
.Lmy_att_preamble:
	v_readlane_b32 s6, v255, 21
	s_load_dword s4, s[72:73], 0x0
	v_mov_b32_e32 v4, v0
	v_cvt_f32_u32_e32 v1, s6
	v_mov_b32_e32 v2, 0x3f4ccccd
	s_waitcnt lgkmcnt(0)
	v_mul_f32_e32 v1, 0xbedd9914, v1
	v_exp_f32_e32 v1, v1
	v_readlane_b32 s7, v255, 22
	v_readfirstlane_b32 s4, v4
	s_mul_i32 s33, s6, 40
	v_fmamk_f32 v1, v1, 0xbf19999a, v2
	v_and_b32_e32 v2, 63, v4
	s_lshl_b64 s[2:3], s[6:7], 10
	s_lshl_b64 s[72:73], s[6:7], 9
	s_waitcnt vmcnt(0)
	v_sub_f32_e32 v182, 1.0, v1
	s_ashr_i32 s94, s4, 6
	s_mov_b32 s6, 0
	s_mov_b32 s101, 0
	v_lshlrev_b32_e32 v172, 2, v2
	s_cmp_lg_u32 s99, 0
	s_cbranch_scc1 .LBB0_549
	s_bfe_u32 s4, s66, 0x30003
	s_cmp_lt_u32 s4, 3
	s_cbranch_scc0 .LBB0_549
	s_mov_b32 s99, 1
	v_writelane_b32 v255, s33, 25
	v_writelane_b32 v255, s94, 27
	s_nop 1
	s_branch .LBB0_749
	s_branch .LBB0_549

; __device__ __forceinline__ unsigned xb_xcc_id() { return (unsigned)__builtin_amdgcn_s_getreg((3 << 11) | 20) & 0xFu; }
; #define ARG_WS() ((unsigned char*)karg64(8 * 19))
; #define WV_DRAW(cls, q, n) int it = 0; if (__builtin_amdgcn_mbcnt_hi(~0u, __builtin_amdgcn_mbcnt_lo(~0u, 0u)) == 0u) it = (int)__hip_atomic_fetch_add(XQ_HEAD(cls, q), (unsigned)(n), RLX_AGENT); it = __builtin_amdgcn_readfirstlane(it);
; template <int ATTM> __device__ __forceinline__ void attention_phase(int layer, int lane, int rep, LAS unsigned char* lds, int wave) {
;     ...
;     if ((ATTM & 8) && PK(8)) {
; #pragma unroll 1
;         for (int qq = 0; qq < 8; ++qq) { const int q = ((int)(xb_xcc_id() & 7u) + qq) & 7;
;             for (;;) { WV_DRAW(3, q, 1); if (it >= 96) break; unsigned char* ws = ARG_WS();
;                 const int chunk = 3 * q + it / 32, idx = (chunk & 3) * 32 + (it & 31);
;                 dil_item_mfma(WSP(bf16, WS_PROJ), ws + WS_VTB, WSP(bf16, WS_O), lds + wave * 16384, chunk >> 2, idx & 15, idx >> 4, lane); } } }
.LBB0_876:
	s_cmp_eq_u32 s99, 1
	s_cbranch_scc0 .Lmy_df_cont
	s_mov_b32 s99, 2
	s_branch .Lmy_att_preamble
